# v61 + gla gate stage (both passes): 8 serial ds_read_b32->wait->compute steps replaced by 8 reads issued together into free VGPRs and one wait
# speedup vs baseline: 1.0222x; 1.0017x over previous
; #define LAS __attribute__((address_space(3)))
; __device__ __forceinline__ float fexp(float x) { return __builtin_amdgcn_exp2f(x * 1.4426950408889634f); }
; __device__ __forceinline__ float flog(float x) { return __builtin_amdgcn_logf(x) * 0.6931471805599453f; }
; __device__ __forceinline__ unsigned pk2(float lo, float hi) { unsigned r; asm("v_cvt_pk_bf16_f32 %0, %1, %2" : "=v"(r) : "v"(lo), "v"(hi)); return r; }
; template <int PASS>
; __device__ __forceinline__ void gla_pass(CArgs& a, LAS unsigned char* lds, int l, int panel) {
;     ...
;         float gl[8];
; #pragma unroll
;         for (int i = 0; i < 8; ++i) {
;             const float x = bg + *(const LAS float*)(lds + GL_X + ((tq * 8 + i) * GXS + d_) * 4);
;             const float ls = fminf(x, 0.f) - flog(1.f + fexp(-fabsf(x)));
;             gl[i] = ls * 0.0625f + (i ? gl[i - 1] : 0.f);
;         }
;         GP[tq * 64 + d_] = gl[7];
;         __syncthreads();
;         float off = 0.f, tot = 0.f;
; #pragma unroll
;         for (int k = 0; k < 8; ++k) { const float v = GP[k * 64 + d_]; tot += v; if (k < tq) off += v; }
;         float kd[8];
; #pragma unroll
;         for (int i = 0; i < 8; ++i) {
;             const float bc = off + gl[i];
;             if (PASS == 2) {
;                 const float eb = fexp(bc);
;                 const unsigned qk = pk2(qv[i] * 0.125f * eb, kv[i] * __builtin_amdgcn_rcpf(eb));
;                 *(LAS bf16_t*)(lds + GL_QE + (tq * 8 + i) * GRS + d_ * 2) = (bf16_t)(qk & 0xffffu);
;                 *(LAS bf16_t*)(lds + GL_KE + (tq * 8 + i) * GRS + d_ * 2) = (bf16_t)(qk >> 16);
;             }
;             kd[i] = kv[i] * fexp(tot - bc);
;         }
;         { u32x4 w; w.x = pk2(kd[0], kd[1]); w.y = pk2(kd[2], kd[3]); w.z = pk2(kd[4], kd[5]); w.w = pk2(kd[6], kd[7]);
;           *(LAS u32x4*)(lds + GL_KDT + d_ * GRS + tq * 16) = w; }
;         if (tq == 0) DK[d_] = fexp(tot);
.LBB0_238:
	v_lshlrev_b32_e32 v102, 16, v44
	ds_read_b32 v218, v60
	v_add_u32_e32 v219, s92, v56
	ds_read_b32 v219, v219
	ds_read_b32 v220, v61
	ds_read_b32 v223, v62
	ds_read_b32 v224, v63
	ds_read_b32 v225, v64
	ds_read_b32 v226, v65
	ds_read_b32 v191, v66
	v_lshlrev_b32_e32 v101, 16, v45
	v_lshlrev_b32_e32 v100, 16, v93
	v_lshlrev_b32_e32 v93, 16, v97
	v_lshlrev_b32_e32 v0, 16, v99
	s_waitcnt lgkmcnt(0)
	v_add_f32_e32 v44, v67, v218
	v_min_f32_e32 v45, 0, v44
	v_mul_f32_e64 v44, |v44|, s33
	v_exp_f32_e32 v44, v44
	v_lshlrev_b32_e32 v98, 16, v94
	v_lshlrev_b32_e32 v94, 16, v96
	v_lshlrev_b32_e32 v95, 16, v95
	v_add_f32_e32 v44, 1.0, v44
	v_log_f32_e32 v44, v44
	s_nop 0
	v_fmac_f32_e32 v45, 0xbf317218, v44
	v_fma_f32 v44, v45, s35, 0
	v_add_f32_e32 v45, v67, v219
	v_min_f32_e32 v97, 0, v45
	v_mul_f32_e64 v45, |v45|, s33
	v_exp_f32_e32 v45, v45
	s_nop 0
	v_add_f32_e32 v45, 1.0, v45
	v_log_f32_e32 v45, v45
	s_nop 0
	v_fmac_f32_e32 v97, 0xbf317218, v45
	v_add_f32_e32 v45, v67, v220
	v_min_f32_e32 v99, 0, v45
	v_mul_f32_e64 v45, |v45|, s33
	v_exp_f32_e32 v45, v45
	s_nop 0
	v_add_f32_e32 v45, 1.0, v45
	v_log_f32_e32 v96, v45
	s_nop 0
	v_pk_mul_f32 v[96:97], v[96:97], s[34:35]
	s_nop 0
	v_sub_f32_e32 v45, v99, v96
	v_add_f32_e32 v97, v44, v97
	v_fmamk_f32 v96, v45, 0x3d800000, v97
	v_add_f32_e32 v45, v67, v223
	v_min_f32_e32 v105, 0, v45
	v_mul_f32_e64 v45, |v45|, s33
	v_exp_f32_e32 v45, v45
	s_nop 0
	v_add_f32_e32 v45, 1.0, v45
	v_log_f32_e32 v45, v45
	s_nop 0
	v_fmac_f32_e32 v105, 0xbf317218, v45
	v_add_f32_e32 v45, v67, v224
	v_min_f32_e32 v99, 0, v45
	v_mul_f32_e64 v45, |v45|, s33
	v_exp_f32_e32 v45, v45
	s_nop 0
	v_add_f32_e32 v45, 1.0, v45
	v_log_f32_e32 v104, v45
	s_nop 0
	v_pk_mul_f32 v[104:105], v[104:105], s[34:35]
	s_nop 0
	v_sub_f32_e32 v45, v99, v104
	v_add_f32_e32 v103, v96, v105
	v_fmamk_f32 v99, v45, 0x3d800000, v103
	v_add_f32_e32 v45, v67, v225
	v_min_f32_e32 v105, 0, v45
	v_mul_f32_e64 v45, |v45|, s33
	v_exp_f32_e32 v45, v45
	s_nop 0
	v_add_f32_e32 v45, 1.0, v45
	v_log_f32_e32 v45, v45
	s_nop 0
	v_fmac_f32_e32 v105, 0xbf317218, v45
	v_add_f32_e32 v45, v67, v226
	v_min_f32_e32 v106, 0, v45
	v_mul_f32_e64 v45, |v45|, s33
	v_exp_f32_e32 v45, v45
	s_nop 0
	v_add_f32_e32 v45, 1.0, v45
	v_log_f32_e32 v104, v45
	s_nop 0
	v_pk_mul_f32 v[104:105], v[104:105], s[34:35]
	s_nop 0
	v_sub_f32_e32 v45, v106, v104
	v_add_f32_e32 v110, v99, v105
	v_fmamk_f32 v105, v45, 0x3d800000, v110
	v_add_f32_e32 v104, v67, v191
	v_min_f32_e32 v106, 0, v104
	v_mul_f32_e64 v104, |v104|, s33
	v_exp_f32_e32 v104, v104
	s_nop 0
	v_add_f32_e32 v104, 1.0, v104
	v_log_f32_e32 v104, v104
	s_nop 0
	v_fmac_f32_e32 v106, 0xbf317218, v104
	v_fmamk_f32 v111, v106, 0x3d800000, v105
	ds_write_b32 v49, v111
	s_waitcnt lgkmcnt(0)
	s_barrier
	ds_read2st64_b32 v[106:107], v50 offset1:1
	s_waitcnt lgkmcnt(0)
	v_add_f32_e32 v45, 0, v106
	v_cndmask_b32_e64 v104, 0, v45, s[44:45]
	v_add_f32_e32 v106, v107, v104
	v_add_f32_e32 v45, v45, v107
	v_cndmask_b32_e64 v104, v104, v106, s[46:47]
	ds_read2st64_b32 v[106:107], v50 offset0:2 offset1:3
	s_waitcnt lgkmcnt(0)
	v_add_f32_e32 v45, v45, v106
	v_add_f32_e32 v106, v106, v104
	v_cndmask_b32_e64 v104, v104, v106, s[48:49]
	v_add_f32_e32 v106, v107, v104
	v_add_f32_e32 v45, v45, v107
	v_cndmask_b32_e64 v104, v104, v106, s[50:51]
	ds_read2st64_b32 v[106:107], v50 offset0:4 offset1:5
	s_waitcnt lgkmcnt(0)
	v_add_f32_e32 v45, v45, v106
	v_add_f32_e32 v106, v106, v104
	v_cndmask_b32_e64 v104, v104, v106, s[52:53]
	v_add_f32_e32 v106, v107, v104
	v_add_f32_e32 v45, v45, v107
	v_cndmask_b32_e64 v108, v104, v106, s[54:55]
	ds_read2st64_b32 v[106:107], v50 offset0:6 offset1:7
	s_waitcnt lgkmcnt(0)
	v_add_f32_e32 v104, v45, v106
	v_add_f32_e32 v45, v106, v108
	v_cndmask_b32_e64 v45, v108, v45, s[56:57]
	v_add_f32_e32 v106, v107, v45
	v_cndmask_b32_e64 v109, v45, v106, s[58:59]
	v_mov_b32_e32 v108, v107
	v_add_f32_e32 v106, v44, v109
	v_pk_add_f32 v[44:45], v[104:105], v[108:109]
	v_add_f32_e32 v96, v96, v109
	v_add_f32_e32 v99, v99, v109
	v_sub_f32_e32 v45, v44, v45
	v_sub_f32_e32 v96, v44, v96
	v_sub_f32_e32 v99, v44, v99
	v_mul_f32_e32 v45, 0x3fb8aa3b, v45
	v_mul_f32_e32 v96, 0x3fb8aa3b, v96
	v_mul_f32_e32 v99, 0x3fb8aa3b, v99
	v_exp_f32_e32 v45, v45
	v_exp_f32_e32 v96, v96
	v_exp_f32_e32 v99, v99
	v_add_f32_e32 v97, v97, v109
	v_mul_f32_e32 v45, v45, v93
	v_add_f32_e32 v93, v111, v109
	v_sub_f32_e32 v97, v44, v97
	v_mul_f32_e32 v96, v96, v100
	v_add_f32_e32 v100, v103, v109
	v_mul_f32_e32 v99, v99, v95
	v_add_f32_e32 v95, v110, v109
	v_sub_f32_e32 v93, v44, v93
	v_sub_f32_e32 v104, v44, v106
	v_mul_f32_e32 v97, 0x3fb8aa3b, v97
	v_sub_f32_e32 v100, v44, v100
	v_sub_f32_e32 v95, v44, v95
	v_mul_f32_e32 v93, 0x3fb8aa3b, v93
	v_mul_f32_e32 v104, 0x3fb8aa3b, v104
	v_exp_f32_e32 v97, v97
	v_mul_f32_e32 v100, 0x3fb8aa3b, v100
	v_mul_f32_e32 v95, 0x3fb8aa3b, v95
	v_exp_f32_e32 v93, v93
	v_exp_f32_e32 v104, v104
	v_exp_f32_e32 v100, v100
	v_exp_f32_e32 v95, v95
	v_mul_f32_e32 v97, v97, v101
	v_mul_f32_e32 v0, v93, v0
	v_mul_f32_e32 v102, v104, v102
	v_mul_f32_e32 v98, v100, v98
	v_mul_f32_e32 v100, v95, v94
	v_cvt_pk_bf16_f32 v94, v102, v97
	v_cvt_pk_bf16_f32 v97, v45, v0
	v_add_u32_e32 v0, v52, v53
	v_cvt_pk_bf16_f32 v95, v96, v98
	v_cvt_pk_bf16_f32 v96, v99, v100
	ds_write_b128 v0, v[94:97] offset:18432
	s_and_saveexec_b64 s[8:9], s[42:43]
	s_cbranch_execz .LBB0_240
	v_mul_f32_e32 v0, 0x3fb8aa3b, v44
	v_exp_f32_e32 v0, v0
	ds_write_b32 v54, v0

; #define LAS __attribute__((address_space(3)))
; __device__ __forceinline__ float fexp(float x) { return __builtin_amdgcn_exp2f(x * 1.4426950408889634f); }
; __device__ __forceinline__ float flog(float x) { return __builtin_amdgcn_logf(x) * 0.6931471805599453f; }
; __device__ __forceinline__ float bf1(bf16_t v) { return __uint_as_float(((unsigned)v) << 16); }
; template <int PASS>
; __device__ __forceinline__ void gla_pass(CArgs& a, LAS unsigned char* lds, int l, int panel) {
;     ...
;         for (int i = 0; i < 8; ++i) { qv[i] = (PASS == 2) ? bf1(pq[i]) : 0.f; kv[i] = bf1(pk[i]); vpk[i] = pv[i]; }
; #pragma unroll
;         for (int k = 0; k < 4; ++k) rvv[k] = pr[k];
;         if (it + 1 < 16) GLA_LOAD(it + 1);
;         float gl[8];
; #pragma unroll
;         for (int i = 0; i < 8; ++i) {
;             const float x = bg + *(const LAS float*)(lds + GL_X + ((tq * 8 + i) * GXS + d_) * 4);
;             const float ls = fminf(x, 0.f) - flog(1.f + fexp(-fabsf(x)));
;             gl[i] = ls * 0.0625f + (i ? gl[i - 1] : 0.f);
;         }
;         GP[tq * 64 + d_] = gl[7];
;         __syncthreads();
.LBB0_384:
	v_lshlrev_b32_e32 v73, 16, v46
	ds_read_b32 v218, v184
	v_add_u32_e32 v219, s92, v169
	ds_read_b32 v219, v219
	ds_read_b32 v220, v185
	ds_read_b32 v223, v186
	ds_read_b32 v224, v187
	ds_read_b32 v225, v188
	ds_read_b32 v226, v190
	ds_read_b32 v191, v192
	v_lshlrev_b32_e32 v72, 16, v47
	v_lshlrev_b32_e32 v71, 16, v48
	v_lshlrev_b32_e32 v77, 16, v61
	v_lshlrev_b32_e32 v61, 16, v63
	s_waitcnt lgkmcnt(0)
	v_add_f32_e32 v46, v174, v218
	v_min_f32_e32 v47, 0, v46
	v_mul_f32_e64 v46, |v46|, s33
	v_exp_f32_e32 v46, v46
	v_lshlrev_b32_e32 v70, 16, v49
	v_lshlrev_b32_e32 v49, 16, v66
	v_lshlrev_b32_e32 v75, 16, v59
	v_add_f32_e32 v46, 1.0, v46
	v_log_f32_e32 v46, v46
	v_lshlrev_b32_e32 v59, 16, v64
	v_lshlrev_b32_e32 v0, 16, v65
	v_lshlrev_b32_e32 v76, 16, v60
	v_fmac_f32_e32 v47, 0xbf317218, v46
	v_fma_f32 v48, v47, s35, 0
	v_lshlrev_b32_e32 v60, 16, v68
	v_lshlrev_b32_e32 v74, 16, v58
	v_lshlrev_b32_e32 v58, 16, v69
	v_add_f32_e32 v46, v174, v219
	v_min_f32_e32 v47, 0, v46
	v_mul_f32_e64 v46, |v46|, s33
	v_exp_f32_e32 v46, v46
	v_lshlrev_b32_e32 v67, 16, v67
	v_mul_f32_e32 v79, 0x3e000000, v67
	v_mul_f32_e32 v78, 0x3e000000, v49
	v_add_f32_e32 v46, 1.0, v46
	v_log_f32_e32 v46, v46
	v_mul_f32_e32 v74, 0x3e000000, v74
	v_mul_f32_e32 v75, 0x3e000000, v75
	v_mul_f32_e32 v76, 0x3e000000, v76
	v_fmac_f32_e32 v47, 0xbf317218, v46
	v_mul_f32_e32 v77, 0x3e000000, v77
	v_lshlrev_b32_e32 v62, 16, v62
	v_mul_f32_e32 v60, 0x3e000000, v60
	v_mul_f32_e32 v58, 0x3e000000, v58
	v_add_f32_e32 v46, v174, v220
	v_min_f32_e32 v63, 0, v46
	v_mul_f32_e64 v46, |v46|, s33
	v_exp_f32_e32 v46, v46
	s_nop 0
	v_add_f32_e32 v46, 1.0, v46
	v_log_f32_e32 v46, v46
	s_nop 0
	v_pk_mul_f32 v[46:47], v[46:47], s[34:35]
	s_nop 0
	v_sub_f32_e32 v46, v63, v46
	v_add_f32_e32 v66, v48, v47
	v_fmamk_f32 v64, v46, 0x3d800000, v66
	v_add_f32_e32 v46, v174, v223
	v_min_f32_e32 v47, 0, v46
	v_mul_f32_e64 v46, |v46|, s33
	v_exp_f32_e32 v46, v46
	s_nop 0
	v_add_f32_e32 v46, 1.0, v46
	v_log_f32_e32 v46, v46
	s_nop 0
	v_fmac_f32_e32 v47, 0xbf317218, v46
	v_add_f32_e32 v46, v174, v224
	v_min_f32_e32 v63, 0, v46
	v_mul_f32_e64 v46, |v46|, s33
	v_exp_f32_e32 v46, v46
	s_nop 0
	v_add_f32_e32 v46, 1.0, v46
	v_log_f32_e32 v46, v46
	s_nop 0
	v_pk_mul_f32 v[46:47], v[46:47], s[34:35]
	s_nop 0
	v_sub_f32_e32 v46, v63, v46
	v_add_f32_e32 v65, v64, v47
	v_fmamk_f32 v63, v46, 0x3d800000, v65
	v_add_f32_e32 v46, v174, v225
	v_min_f32_e32 v47, 0, v46
	v_mul_f32_e64 v46, |v46|, s33
	v_exp_f32_e32 v46, v46
	s_nop 0
	v_add_f32_e32 v46, 1.0, v46
	v_log_f32_e32 v46, v46
	s_nop 0
	v_fmac_f32_e32 v47, 0xbf317218, v46
	v_add_f32_e32 v46, v174, v226
	v_min_f32_e32 v68, 0, v46
	v_mul_f32_e64 v46, |v46|, s33
	v_exp_f32_e32 v46, v46
	s_nop 0
	v_add_f32_e32 v46, 1.0, v46
	v_log_f32_e32 v46, v46
	s_nop 0
	v_pk_mul_f32 v[46:47], v[46:47], s[34:35]
	s_nop 0
	v_sub_f32_e32 v46, v68, v46
	v_add_f32_e32 v80, v63, v47
	v_fmamk_f32 v47, v46, 0x3d800000, v80
	v_add_f32_e32 v68, v174, v191
	v_min_f32_e32 v69, 0, v68
	v_mul_f32_e64 v68, |v68|, s33
	v_exp_f32_e32 v68, v68
	s_nop 0
	v_add_f32_e32 v68, 1.0, v68
	v_log_f32_e32 v68, v68
	s_nop 0
	v_fmac_f32_e32 v69, 0xbf317218, v68
	v_fmamk_f32 v67, v69, 0x3d800000, v47
	ds_write_b32 v154, v67
	s_waitcnt lgkmcnt(0)
	s_barrier
; #define LAS __attribute__((address_space(3)))
; __device__ __forceinline__ float fexp(float x) { return __builtin_amdgcn_exp2f(x * 1.4426950408889634f); }
; __device__ __forceinline__ unsigned pk2(float lo, float hi) { unsigned r; asm("v_cvt_pk_bf16_f32 %0, %1, %2" : "=v"(r) : "v"(lo), "v"(hi)); return r; }
; template <int PASS>
; __device__ __forceinline__ void gla_pass(CArgs& a, LAS unsigned char* lds, int l, int panel) {
;     ...
;         float off = 0.f, tot = 0.f;
; #pragma unroll
;         for (int k = 0; k < 8; ++k) { const float v = GP[k * 64 + d_]; tot += v; if (k < tq) off += v; }
;         float kd[8];
; #pragma unroll
;         for (int i = 0; i < 8; ++i) {
;             const float bc = off + gl[i];
;             if (PASS == 2) {
;                 const float eb = fexp(bc);
;                 const unsigned qk = pk2(qv[i] * 0.125f * eb, kv[i] * __builtin_amdgcn_rcpf(eb));
;                 *(LAS bf16_t*)(lds + GL_QE + (tq * 8 + i) * GRS + d_ * 2) = (bf16_t)(qk & 0xffffu);
;                 *(LAS bf16_t*)(lds + GL_KE + (tq * 8 + i) * GRS + d_ * 2) = (bf16_t)(qk >> 16);
;             }
;             kd[i] = kv[i] * fexp(tot - bc);
;         }
;         { u32x4 w; w.x = pk2(kd[0], kd[1]); w.y = pk2(kd[2], kd[3]); w.z = pk2(kd[4], kd[5]); w.w = pk2(kd[6], kd[7]);
;           *(LAS u32x4*)(lds + GL_KDT + d_ * GRS + tq * 16) = w; }
;         if (tq == 0) DK[d_] = fexp(tot);
	ds_read2st64_b32 v[68:69], v155 offset1:1
	s_waitcnt lgkmcnt(0)
	v_add_f32_e32 v46, 0, v68
	v_cndmask_b32_e64 v49, 0, v46, s[48:49]
	v_add_f32_e32 v68, v69, v49
	v_add_f32_e32 v46, v46, v69
	v_cndmask_b32_e64 v49, v49, v68, s[50:51]
	ds_read2st64_b32 v[68:69], v155 offset0:2 offset1:3
	s_waitcnt lgkmcnt(0)
	v_add_f32_e32 v46, v46, v68
	v_add_f32_e32 v68, v68, v49
	v_cndmask_b32_e64 v49, v49, v68, s[52:53]
	v_add_f32_e32 v68, v69, v49
	v_add_f32_e32 v46, v46, v69
	v_cndmask_b32_e64 v49, v49, v68, s[54:55]
	ds_read2st64_b32 v[68:69], v155 offset0:4 offset1:5
	s_waitcnt lgkmcnt(0)
	v_add_f32_e32 v46, v46, v68
	v_add_f32_e32 v68, v68, v49
	v_cndmask_b32_e64 v49, v49, v68, s[56:57]
	v_add_f32_e32 v68, v69, v49
	v_add_f32_e32 v46, v46, v69
	v_cndmask_b32_e64 v49, v49, v68, s[58:59]
	ds_read2st64_b32 v[68:69], v155 offset0:6 offset1:7
	s_waitcnt lgkmcnt(0)
	v_add_f32_e32 v46, v46, v68
	v_add_f32_e32 v68, v68, v49
	v_cndmask_b32_e64 v49, v49, v68, s[60:61]
	v_add_f32_e32 v68, v69, v49
	v_cndmask_b32_e64 v49, v49, v68, s[62:63]
	v_add_f32_e32 v68, v48, v49
	v_mul_f32_e32 v48, 0x3fb8aa3b, v68
	v_exp_f32_e32 v48, v48
	v_add_f32_e32 v66, v66, v49
	v_add_f32_e32 v64, v64, v49
	v_add_f32_e32 v65, v65, v49
	v_mul_f32_e32 v74, v74, v48
	v_rcp_f32_e32 v48, v48
	v_add_f32_e32 v63, v63, v49
	v_mul_f32_e32 v48, v48, v73
	v_cvt_pk_bf16_f32 v48, v74, v48
	ds_write_b16 v172, v48
	ds_write_b16_d16_hi v172, v48 offset:9216
	v_mov_b32_e32 v48, v69
	v_pk_add_f32 v[46:47], v[46:47], v[48:49]
	s_nop 0
	v_sub_f32_e32 v48, v46, v68
	v_mul_f32_e32 v68, 0x3fb8aa3b, v66
	v_exp_f32_e32 v68, v68
	v_sub_f32_e32 v66, v46, v66
	v_mul_f32_e32 v48, 0x3fb8aa3b, v48
	v_mul_f32_e32 v66, 0x3fb8aa3b, v66
	v_mul_f32_e32 v69, v75, v68
	v_rcp_f32_e32 v68, v68
	v_exp_f32_e32 v48, v48
	v_exp_f32_e32 v66, v66
	v_mul_f32_e32 v68, v68, v72
	v_cvt_pk_bf16_f32 v68, v69, v68
	ds_write_b16 v173, v68
	ds_write_b16_d16_hi v173, v68 offset:9216
	v_mul_f32_e32 v68, 0x3fb8aa3b, v64
	v_exp_f32_e32 v68, v68
	v_sub_f32_e32 v64, v46, v64
	v_mul_f32_e32 v64, 0x3fb8aa3b, v64
	v_exp_f32_e32 v64, v64
	v_mul_f32_e32 v69, v76, v68
	v_rcp_f32_e32 v68, v68
	v_mul_f32_e32 v48, v48, v73
	v_mul_f32_e32 v66, v66, v72
	v_mul_f32_e32 v64, v64, v71
	v_mul_f32_e32 v68, v68, v71
	v_cvt_pk_bf16_f32 v68, v69, v68
	ds_write_b16 v173, v68 offset:144
	ds_write_b16_d16_hi v173, v68 offset:9360
	v_mul_f32_e32 v68, 0x3fb8aa3b, v65
	v_exp_f32_e32 v68, v68
	v_sub_f32_e32 v65, v46, v65
	v_mul_f32_e32 v65, 0x3fb8aa3b, v65
	v_exp_f32_e32 v65, v65
	v_mul_f32_e32 v69, v77, v68
	v_rcp_f32_e32 v68, v68
	v_mul_f32_e32 v65, v65, v70
	v_mul_f32_e32 v68, v68, v70
	v_cvt_pk_bf16_f32 v68, v69, v68
	ds_write_b16 v173, v68 offset:288
	ds_write_b16_d16_hi v173, v68 offset:9504
	v_mul_f32_e32 v68, 0x3fb8aa3b, v63
	v_exp_f32_e32 v68, v68
	v_sub_f32_e32 v63, v46, v63
	v_mul_f32_e32 v63, 0x3fb8aa3b, v63
	v_exp_f32_e32 v63, v63
	v_mul_f32_e32 v69, v78, v68
	v_rcp_f32_e32 v68, v68
	s_nop 0
	v_mul_f32_e32 v68, v68, v62
	v_cvt_pk_bf16_f32 v68, v69, v68
	v_mul_f32_e32 v62, v63, v62
	v_add_f32_e32 v63, v80, v49
	ds_write_b16 v173, v68 offset:432
	ds_write_b16_d16_hi v173, v68 offset:9648
	v_mul_f32_e32 v68, 0x3fb8aa3b, v63
	v_exp_f32_e32 v68, v68
	v_sub_f32_e32 v63, v46, v63
	v_mul_f32_e32 v63, 0x3fb8aa3b, v63
	v_exp_f32_e32 v63, v63
	v_mul_f32_e32 v69, v79, v68
	v_rcp_f32_e32 v68, v68
	v_add_f32_e32 v49, v67, v49
	v_mul_f32_e32 v68, v68, v61
	v_mul_f32_e32 v61, v63, v61
	v_mul_f32_e32 v63, 0x3fb8aa3b, v47
	v_exp_f32_e32 v63, v63
	v_sub_f32_e32 v47, v46, v47
	v_mul_f32_e32 v47, 0x3fb8aa3b, v47
	v_exp_f32_e32 v47, v47
	v_mul_f32_e32 v60, v60, v63
	v_rcp_f32_e32 v63, v63
	v_cvt_pk_bf16_f32 v68, v69, v68
	v_mul_f32_e32 v47, v47, v59
	ds_write_b16 v173, v68 offset:576
	ds_write_b16_d16_hi v173, v68 offset:9792
	v_mul_f32_e32 v63, v63, v59
	v_mul_f32_e32 v59, 0x3fb8aa3b, v49
	v_exp_f32_e32 v59, v59
	v_sub_f32_e32 v49, v46, v49
	v_mul_f32_e32 v49, 0x3fb8aa3b, v49
	v_exp_f32_e32 v49, v49
	v_mul_f32_e32 v58, v58, v59
	v_rcp_f32_e32 v59, v59
	v_cvt_pk_bf16_f32 v60, v60, v63
	ds_write_b16 v173, v60 offset:720
	ds_write_b16_d16_hi v173, v60 offset:9936
	v_cvt_pk_bf16_f32 v60, v62, v61
	v_mul_f32_e32 v59, v59, v0
	v_mul_f32_e32 v0, v49, v0
	v_cvt_pk_bf16_f32 v58, v58, v59
	v_cvt_pk_bf16_f32 v61, v47, v0
	v_add_u32_e32 v0, v156, v157
	ds_write_b16 v173, v58 offset:864
	ds_write_b16_d16_hi v173, v58 offset:10080
	v_cvt_pk_bf16_f32 v58, v48, v66
	v_cvt_pk_bf16_f32 v59, v64, v65
	ds_write_b128 v0, v[58:61] offset:18432
	s_and_saveexec_b64 s[8:9], s[42:43]
	s_cbranch_execz .LBB0_386
	v_mul_f32_e32 v0, 0x3fb8aa3b, v46
	v_exp_f32_e32 v0, v0
	ds_write_b32 v158, v0
